# MLA attention output epilogue: dwordx2 store pairs -> dwordx4 via permlane16_swap row exchange
# baseline (speedup 1.0000x reference)
; __device__ __forceinline__ unsigned pk2(float lo, float hi) { f32x2_t v = {lo, hi}; bf16x2_t b = __builtin_convertvector(v, bf16x2_t); return __builtin_bit_cast(unsigned, b); }
; __device__ __forceinline__ float xor16_sum(float v) { float a = v, b = v; swap16(a, b); return a + b; }
; __device__ __forceinline__ float xor32_sum(float v) { float a = v, b = v; swap32(a, b); return a + b; }
; template <int DQK, int QF>
; __device__ __forceinline__ void attn_unit_dma(LAS unsigned char* lds, const bf16_t* Qp, int ldq, const bf16_t* Kp, int ldk, const bf16_t* VTp, int ldvt, bf16_t* Op, int ldo, int nkt, int wave_last, const float* qgam, float qscale) {
;     ...
; #pragma unroll
;     for (int qf = 0; qf < QF; ++qf) {
;         float l = lrun[qf]; l = xor16_sum(l); l = xor32_sum(l);
;         const float inv = 1.f / l;
;         bf16_t* op = Op + (size_t)(16 * QF * wid + 16 * qf + fr) * ldo + 4 * fq;
; #pragma unroll
;         for (int mv = 0; mv < 8; ++mv) { u32x2 w; w.x = pk2(o[qf][mv][0] * inv, o[qf][mv][1] * inv); w.y = pk2(o[qf][mv][2] * inv, o[qf][mv][3] * inv); *(u32x2*)(op + 16 * mv) = w; }
;     }
.LBB0_1061:
	s_waitcnt vmcnt(0)
	v_mov_b32_e32 v0, v207
	s_nop 1
	v_permlane16_swap_b32 v207, v0
	v_mov_b32_e32 v199, v189
	v_add_f32_e32 v0, v207, v0
	v_mov_b32_e32 v1, v0
	s_nop 1
	v_permlane32_swap_b32 v1, v0
	s_xor_b64 s[12:13], s[42:43], -1
	v_add_f32_e32 v2, v1, v0
	v_div_scale_f32 v3, s[16:17], v2, v2, 1.0
	v_rcp_f32_e32 v4, v3
	s_lshl_b64 s[16:17], s[38:39], 12
	v_lshl_add_u64 v[0:1], v[196:197], 0, s[16:17]
	s_mov_b64 s[42:43], 0
	v_fma_f32 v5, -v3, v4, 1.0
	v_fmac_f32_e32 v4, v5, v4
	v_div_scale_f32 v5, vcc, 1.0, v2, 1.0
	v_mul_f32_e32 v6, v5, v4
	v_fma_f32 v7, -v3, v6, v5
	v_fmac_f32_e32 v6, v7, v4
	v_fma_f32 v3, -v3, v6, v5
	v_div_fmas_f32 v3, v3, v4, v6
	v_div_fixup_f32 v2, v3, v2, 1.0
	v_lshlrev_b64 v[4:5], 12, v[188:189]
	v_lshl_add_u64 v[4:5], v[0:1], 0, v[4:5]
	v_bfe_u32 v14, v184, 4, 1
	v_mul_u32_u24_e32 v14, 24, v14
	v_mov_b32_e32 v15, 0
	v_lshl_add_u64 v[14:15], v[4:5], 0, v[14:15]
	v_pk_mul_f32 v[10:11], v[100:101], v[2:3] op_sel_hi:[1,0]
	v_pk_mul_f32 v[12:13], v[102:103], v[2:3] op_sel_hi:[1,0]
	v_pk_mul_f32 v[6:7], v[96:97], v[2:3] op_sel_hi:[1,0]
	v_pk_mul_f32 v[8:9], v[98:99], v[2:3] op_sel_hi:[1,0]
	v_cvt_pk_bf16_f32 v6, v6, v7
	v_cvt_pk_bf16_f32 v7, v8, v9
	v_cvt_pk_bf16_f32 v8, v10, v11
	v_cvt_pk_bf16_f32 v9, v12, v13
	s_nop 1
	v_permlane16_swap_b32 v6, v8
	v_permlane16_swap_b32 v7, v9
	global_store_dwordx4 v[14:15], v[6:9], off
	v_pk_mul_f32 v[10:11], v[84:85], v[2:3] op_sel_hi:[1,0]
	v_pk_mul_f32 v[12:13], v[86:87], v[2:3] op_sel_hi:[1,0]
	v_pk_mul_f32 v[6:7], v[92:93], v[2:3] op_sel_hi:[1,0]
	v_pk_mul_f32 v[8:9], v[94:95], v[2:3] op_sel_hi:[1,0]
	v_cvt_pk_bf16_f32 v6, v6, v7
	v_cvt_pk_bf16_f32 v7, v8, v9
	v_cvt_pk_bf16_f32 v8, v10, v11
	v_cvt_pk_bf16_f32 v9, v12, v13
	s_nop 1
	v_permlane16_swap_b32 v6, v8
	v_permlane16_swap_b32 v7, v9
	global_store_dwordx4 v[14:15], v[6:9], off offset:64
	v_pk_mul_f32 v[10:11], v[104:105], v[2:3] op_sel_hi:[1,0]
	v_pk_mul_f32 v[12:13], v[106:107], v[2:3] op_sel_hi:[1,0]
	v_pk_mul_f32 v[6:7], v[88:89], v[2:3] op_sel_hi:[1,0]
	v_pk_mul_f32 v[8:9], v[90:91], v[2:3] op_sel_hi:[1,0]
	v_cvt_pk_bf16_f32 v6, v6, v7
	v_cvt_pk_bf16_f32 v7, v8, v9
	v_cvt_pk_bf16_f32 v8, v10, v11
	v_cvt_pk_bf16_f32 v9, v12, v13
	s_nop 1
	v_permlane16_swap_b32 v6, v8
	v_permlane16_swap_b32 v7, v9
	global_store_dwordx4 v[14:15], v[6:9], off offset:128
	s_nop 1
	v_pk_mul_f32 v[6:7], v[108:109], v[2:3] op_sel_hi:[1,0]
	v_pk_mul_f32 v[8:9], v[110:111], v[2:3] op_sel_hi:[1,0]
	v_cvt_pk_bf16_f32 v6, v6, v7
	v_cvt_pk_bf16_f32 v7, v8, v9
	global_store_dwordx2 v[4:5], v[6:7], off offset:192
	v_pk_mul_f32 v[6:7], v[48:49], v[2:3] op_sel_hi:[1,0]
	v_mov_b32_e32 v3, v206
	s_nop 1
	v_permlane16_swap_b32 v206, v3
	v_cvt_pk_bf16_f32 v6, v6, v7
	v_add_f32_e32 v3, v206, v3
	v_mov_b32_e32 v7, v3
	s_nop 1
	v_permlane32_swap_b32 v7, v3
	s_nop 0
	v_add_f32_e32 v8, v7, v3
	v_div_scale_f32 v9, s[16:17], v8, v8, 1.0
	v_rcp_f32_e32 v10, v9
	v_pk_mul_f32 v[2:3], v[50:51], v[2:3] op_sel_hi:[1,0]
	s_nop 0
	v_cvt_pk_bf16_f32 v7, v2, v3
	v_fma_f32 v2, -v9, v10, 1.0
	v_fmac_f32_e32 v10, v2, v10
	v_div_scale_f32 v2, vcc, 1.0, v8, 1.0
	v_mul_f32_e32 v3, v2, v10
	global_store_dwordx2 v[4:5], v[6:7], off offset:224
	v_fma_f32 v4, -v9, v3, v2
	v_fmac_f32_e32 v3, v4, v10
	v_fma_f32 v2, -v9, v3, v2
	v_div_fmas_f32 v2, v2, v10, v3
	v_div_fixup_f32 v2, v2, v8, 1.0
	v_lshlrev_b64 v[4:5], 12, v[198:199]
	v_lshl_add_u64 v[0:1], v[0:1], 0, v[4:5]
	v_bfe_u32 v12, v184, 4, 1
	v_mul_u32_u24_e32 v12, 24, v12
	v_mov_b32_e32 v13, 0
	v_lshl_add_u64 v[12:13], v[0:1], 0, v[12:13]
	v_pk_mul_f32 v[8:9], v[64:65], v[2:3] op_sel_hi:[1,0]
	v_pk_mul_f32 v[10:11], v[66:67], v[2:3] op_sel_hi:[1,0]
	v_pk_mul_f32 v[4:5], v[68:69], v[2:3] op_sel_hi:[1,0]
	v_pk_mul_f32 v[6:7], v[70:71], v[2:3] op_sel_hi:[1,0]
	v_cvt_pk_bf16_f32 v4, v4, v5
	v_cvt_pk_bf16_f32 v5, v6, v7
	v_cvt_pk_bf16_f32 v6, v8, v9
	v_cvt_pk_bf16_f32 v7, v10, v11
	s_nop 1
	v_permlane16_swap_b32 v4, v6
	v_permlane16_swap_b32 v5, v7
	global_store_dwordx4 v[12:13], v[4:7], off
	v_pk_mul_f32 v[8:9], v[56:57], v[2:3] op_sel_hi:[1,0]
	v_pk_mul_f32 v[10:11], v[58:59], v[2:3] op_sel_hi:[1,0]
	v_pk_mul_f32 v[4:5], v[60:61], v[2:3] op_sel_hi:[1,0]
	v_pk_mul_f32 v[6:7], v[62:63], v[2:3] op_sel_hi:[1,0]
	v_cvt_pk_bf16_f32 v4, v4, v5
	v_cvt_pk_bf16_f32 v5, v6, v7
	v_cvt_pk_bf16_f32 v6, v8, v9
	v_cvt_pk_bf16_f32 v7, v10, v11
	s_nop 1
	v_permlane16_swap_b32 v4, v6
	v_permlane16_swap_b32 v5, v7
	global_store_dwordx4 v[12:13], v[4:7], off offset:64
	v_pk_mul_f32 v[8:9], v[76:77], v[2:3] op_sel_hi:[1,0]
	v_pk_mul_f32 v[10:11], v[78:79], v[2:3] op_sel_hi:[1,0]
	v_pk_mul_f32 v[4:5], v[72:73], v[2:3] op_sel_hi:[1,0]
	v_pk_mul_f32 v[6:7], v[74:75], v[2:3] op_sel_hi:[1,0]
	v_cvt_pk_bf16_f32 v4, v4, v5
	v_cvt_pk_bf16_f32 v5, v6, v7
	v_cvt_pk_bf16_f32 v6, v8, v9
	v_cvt_pk_bf16_f32 v7, v10, v11
	s_nop 1
	v_permlane16_swap_b32 v4, v6
	v_permlane16_swap_b32 v5, v7
	global_store_dwordx4 v[12:13], v[4:7], off offset:128
	v_pk_mul_f32 v[8:9], v[52:53], v[2:3] op_sel_hi:[1,0]
	v_pk_mul_f32 v[10:11], v[54:55], v[2:3] op_sel_hi:[1,0]
	v_pk_mul_f32 v[4:5], v[80:81], v[2:3] op_sel_hi:[1,0]
	v_pk_mul_f32 v[6:7], v[82:83], v[2:3] op_sel_hi:[1,0]
	v_cvt_pk_bf16_f32 v4, v4, v5
	v_cvt_pk_bf16_f32 v5, v6, v7
	v_cvt_pk_bf16_f32 v6, v8, v9
	v_cvt_pk_bf16_f32 v7, v10, v11
	s_nop 1
	v_permlane16_swap_b32 v4, v6
	v_permlane16_swap_b32 v5, v7
	s_and_b64 vcc, exec, s[12:13]
	global_store_dwordx4 v[12:13], v[4:7], off offset:192
	s_cbranch_vccnz .LBB0_1058
